# as version 63 plus gate|up epilogue: packed f32 VALU ops (v_pk_mul_f32 / v_pk_fma_f32) split into single v_mul_f32 / v_fma_f32 (bit-identical)
# speedup vs baseline: 1.0028x; 1.0004x over previous
; __device__ __forceinline__ unsigned cvt2_bf16(float lo, float hi) { const f32x2n v = {lo, hi}; return __builtin_bit_cast(unsigned, __builtin_convertvector(v, bf16x2n)); }
;     __device__ __forceinline__ void operator()(const f32x4 (&acc)[2][2][4][2], const Unit& u, int wr, int wc, int fr, int fq) const {
;     ...
;         const int row0 = u.pm * BM + wr * 64 + fr, col0 = u.pn * HALF + wc * 32 + 8 * fq;
;         float rs[2][4];
; #pragma unroll
;         for (int ai = 0; ai < 2; ++ai)
; #pragma unroll
;             for (int m = 0; m < 4; ++m) rs[ai][m] = rowss[row0 + ai * HALF + m * 16];
; #pragma unroll
;         for (int ai = 0; ai < 2; ++ai)
; #pragma unroll
;             for (int m = 0; m < 4; ++m) {
;                 const int row = row0 + ai * HALF + m * 16;
;                 const float ms = rs[ai][m] * (1.0f / 1024.0f) + RMS_EPS, c1 = -1.4426950408889634f * rsqrtf(ms);
;                 const f32x4 g0 = acc[ai][0][m][0], g1 = acc[ai][0][m][1], u0 = acc[ai][1][m][0], u1 = acc[ai][1][m][1];
;                 const f32x4 t0 = g0 * c1, t1 = g1 * c1; f32x4 e0, e1, i0, i1;
; #pragma unroll
;                 for (int e = 0; e < 4; ++e) { e0[e] = __builtin_amdgcn_exp2f(t0[e]); e1[e] = __builtin_amdgcn_exp2f(t1[e]); }
;                 const f32x4 d0 = e0 * ms + ms, d1 = e1 * ms + ms;
; #pragma unroll
;                 for (int e = 0; e < 4; ++e) { i0[e] = __builtin_amdgcn_rcpf(d0[e]); i1[e] = __builtin_amdgcn_rcpf(d1[e]); }
;                 const f32x4 h0 = (g0 * u0) * i0, h1 = (g1 * u1) * i1;
;                 u32x4 w; w.x = cvt2_bf16(h0[0], h0[1]); w.y = cvt2_bf16(h0[2], h0[3]); w.z = cvt2_bf16(h1[0], h1[1]); w.w = cvt2_bf16(h1[2], h1[3]);
;                 *(u32x4*)(H + (size_t)row * ldh + col0) = w;
.LBB0_157:
	v_lshl_add_u32 v144, s40, 8, v5
	v_ashrrev_i32_e32 v145, 31, v144
	v_lshl_add_u64 v[162:163], v[144:145], 2, s[6:7]
	s_mov_b32 s12, 0x800000
	v_mul_f32_e32 v124, v132, v124
	v_mul_f32_e32 v125, v133, v125
	v_mul_f32_e32 v122, v130, v122
	v_mul_f32_e32 v123, v131, v123
	v_mul_f32_e32 v118, v126, v118
	v_mul_f32_e32 v119, v127, v119
	v_lshl_or_b32 v162, s31, 7, v147
	v_mul_f32_e32 v120, v128, v120
	v_mul_f32_e32 v121, v129, v121
	v_ashrrev_i32_e32 v163, 31, v162
	s_movk_i32 s13, 0x1600
	v_mul_f32_e32 v104, v108, v104
	v_mul_f32_e32 v105, v109, v105
	v_mul_f32_e32 v102, v106, v102
	v_mul_f32_e32 v103, v107, v103
	v_or_b32_e32 v160, 16, v144
	v_mul_f32_e32 v112, v116, v112
	v_mul_f32_e32 v113, v117, v113
	v_mul_f32_e32 v110, v114, v110
	v_mul_f32_e32 v111, v115, v111
	v_mul_f32_e32 v90, v98, v90
	v_mul_f32_e32 v91, v99, v91
	v_or_b32_e32 v158, 32, v144
	v_mul_f32_e32 v92, v100, v92
	v_mul_f32_e32 v93, v101, v93
	v_mul_f32_e32 v88, v96, v88
	v_mul_f32_e32 v89, v97, v89
	v_mul_f32_e32 v86, v94, v86
	v_mul_f32_e32 v87, v95, v87
	v_mul_f32_e32 v74, v82, v74
	v_mul_f32_e32 v75, v83, v75
	v_or_b32_e32 v156, 48, v144
	v_mul_f32_e32 v76, v84, v76
	v_mul_f32_e32 v77, v85, v77
	v_mul_f32_e32 v72, v80, v72
	v_mul_f32_e32 v73, v81, v73
	v_mul_f32_e32 v70, v78, v70
	v_mul_f32_e32 v71, v79, v71
	v_mul_f32_e32 v58, v66, v58
	v_mul_f32_e32 v59, v67, v59
	v_add_u32_e32 v154, 0x80, v144
	v_mul_f32_e32 v60, v68, v60
	v_mul_f32_e32 v61, v69, v61
	v_mul_f32_e32 v56, v64, v56
	v_mul_f32_e32 v57, v65, v57
	v_mul_f32_e32 v54, v62, v54
	v_mul_f32_e32 v55, v63, v55
	v_mul_f32_e32 v42, v50, v42
	v_mul_f32_e32 v43, v51, v43
	v_add_u32_e32 v152, 0x90, v144
	v_mul_f32_e32 v44, v52, v44
	v_mul_f32_e32 v45, v53, v45
	v_mul_f32_e32 v40, v48, v40
	v_mul_f32_e32 v41, v49, v41
	v_mul_f32_e32 v38, v46, v38
	v_mul_f32_e32 v39, v47, v39
	v_mul_f32_e32 v26, v34, v26
	v_mul_f32_e32 v27, v35, v27
	v_add_u32_e32 v150, 0xa0, v144
	v_mul_f32_e32 v28, v36, v28
	v_mul_f32_e32 v29, v37, v29
	v_mul_f32_e32 v24, v32, v24
	v_mul_f32_e32 v25, v33, v25
	v_mul_f32_e32 v22, v30, v22
	v_mul_f32_e32 v23, v31, v23
	v_mul_f32_e32 v10, v18, v10
	v_mul_f32_e32 v11, v19, v11
	v_add_u32_e32 v145, 0xb0, v144
	v_mul_f32_e32 v12, v20, v12
	v_mul_f32_e32 v13, v21, v13
	v_mul_f32_e32 v8, v16, v8
	v_mul_f32_e32 v9, v17, v9
	v_mul_f32_e32 v6, v14, v6
	v_mul_f32_e32 v7, v15, v7
	s_waitcnt vmcnt(0)
	v_fmamk_f32 v164, v226, 0x3a800000, v231
	v_cmp_gt_f32_e32 vcc, s12, v164
	v_mul_f32_e32 v161, 0x4b800000, v164
	s_nop 0
	v_cndmask_b32_e32 v161, v164, v161, vcc
	v_rsq_f32_e32 v161, v161
	s_nop 0
	v_mul_f32_e32 v165, 0x45800000, v161
	v_cndmask_b32_e32 v161, v161, v165, vcc
	v_mul_f32_e32 v166, 0xbfb8aa3b, v161
	v_mul_f32_e32 v168, v132, v166
	v_mul_f32_e32 v169, v133, v166
	v_mul_f32_e32 v170, v130, v166
	v_mul_f32_e32 v171, v131, v166
	v_mul_f32_e32 v172, v128, v166
	v_mul_f32_e32 v173, v129, v166
	v_mul_f32_e32 v167, v127, v166
	v_mul_f32_e32 v166, v126, v166
	v_exp_f32_e32 v170, v170
	v_exp_f32_e32 v166, v166
	v_exp_f32_e32 v171, v171
	v_exp_f32_e32 v167, v167
	v_exp_f32_e32 v168, v168
	v_exp_f32_e32 v172, v172
	v_exp_f32_e32 v169, v169
	v_exp_f32_e32 v173, v173
	v_fma_f32 v170, v164, v170, v164
	v_fma_f32 v171, v164, v171, v164
	v_fma_f32 v168, v164, v168, v164
	v_fma_f32 v169, v164, v169, v164
	v_fma_f32 v172, v164, v172, v164
	v_fma_f32 v173, v164, v173, v164
	v_fma_f32 v165, v164, v167, v164
	v_fma_f32 v164, v164, v166, v164
	v_rcp_f32_e32 v166, v170
	v_rcp_f32_e32 v164, v164
	v_rcp_f32_e32 v167, v171
	v_rcp_f32_e32 v165, v165
	v_rcp_f32_e32 v168, v168
	v_rcp_f32_e32 v169, v169
	v_rcp_f32_e32 v170, v172
	v_rcp_f32_e32 v171, v173
	v_mul_f32_e32 v122, v122, v166
	v_mul_f32_e32 v123, v123, v167
	v_mul_f32_e32 v124, v124, v168
	v_mul_f32_e32 v125, v125, v169
	v_mul_f32_e32 v118, v118, v164
	v_mul_f32_e32 v119, v119, v165
	v_mul_f32_e32 v120, v120, v170
	v_mul_f32_e32 v121, v121, v171
	v_cvt_pk_bf16_f32 v122, v122, v123
	v_cvt_pk_bf16_f32 v123, v124, v125
	v_cvt_pk_bf16_f32 v124, v118, v119
	v_mov_b64_e32 v[118:119], s[86:87]
	v_cvt_pk_bf16_f32 v125, v120, v121
	v_mad_i64_i32 v[126:127], s[10:11], v144, s13, v[118:119]
	v_lshlrev_b64 v[120:121], 1, v[162:163]
	v_lshl_add_u64 v[126:127], v[126:127], 0, v[120:121]
	global_store_dwordx4 v[126:127], v[122:125], off
	s_nop 1
	v_fmamk_f32 v122, v227, 0x3a800000, v231
	v_cmp_gt_f32_e32 vcc, s12, v122
	v_mul_f32_e32 v123, 0x4b800000, v122
	s_nop 0
	v_cndmask_b32_e32 v123, v122, v123, vcc
	v_rsq_f32_e32 v123, v123
	s_nop 0
	v_mul_f32_e32 v124, 0x45800000, v123
	v_cndmask_b32_e32 v123, v123, v124, vcc
	v_mul_f32_e32 v124, 0xbfb8aa3b, v123
	v_mul_f32_e32 v126, v116, v124
	v_mul_f32_e32 v127, v117, v124
	v_mul_f32_e32 v128, v114, v124
	v_mul_f32_e32 v129, v115, v124
	v_mul_f32_e32 v130, v108, v124
	v_mul_f32_e32 v131, v109, v124
	v_mul_f32_e32 v125, v107, v124
	v_mul_f32_e32 v124, v106, v124
	v_exp_f32_e32 v128, v128
	v_exp_f32_e32 v124, v124
	v_exp_f32_e32 v129, v129
	v_exp_f32_e32 v125, v125
	v_exp_f32_e32 v126, v126
	v_exp_f32_e32 v130, v130
	v_exp_f32_e32 v127, v127
	v_exp_f32_e32 v131, v131
	v_fma_f32 v132, v122, v126, v122
	v_fma_f32 v133, v122, v127, v122
	v_fma_f32 v126, v122, v128, v122
	v_fma_f32 v127, v122, v129, v122
	v_fma_f32 v130, v122, v130, v122
	v_fma_f32 v131, v122, v131, v122
	v_fma_f32 v123, v122, v125, v122
	v_fma_f32 v122, v122, v124, v122
	v_rcp_f32_e32 v122, v122
	v_rcp_f32_e32 v123, v123
	v_rcp_f32_e32 v124, v130
	v_rcp_f32_e32 v125, v131
	v_rcp_f32_e32 v126, v126
	v_rcp_f32_e32 v127, v127
	v_rcp_f32_e32 v128, v132
	v_rcp_f32_e32 v129, v133
	v_mul_f32_e32 v106, v104, v124
	v_mul_f32_e32 v107, v105, v125
	v_mul_f32_e32 v104, v102, v122
; __device__ __forceinline__ unsigned cvt2_bf16(float lo, float hi) { const f32x2n v = {lo, hi}; return __builtin_bit_cast(unsigned, __builtin_convertvector(v, bf16x2n)); }
;     __device__ __forceinline__ void operator()(const f32x4 (&acc)[2][2][4][2], const Unit& u, int wr, int wc, int fr, int fq) const {
;     ...
;             for (int m = 0; m < 4; ++m) {
;                 const int row = row0 + ai * HALF + m * 16;
;                 const float ms = rs[ai][m] * (1.0f / 1024.0f) + RMS_EPS, c1 = -1.4426950408889634f * rsqrtf(ms);
;                 const f32x4 g0 = acc[ai][0][m][0], g1 = acc[ai][0][m][1], u0 = acc[ai][1][m][0], u1 = acc[ai][1][m][1];
;                 const f32x4 t0 = g0 * c1, t1 = g1 * c1; f32x4 e0, e1, i0, i1;
; #pragma unroll
;                 for (int e = 0; e < 4; ++e) { e0[e] = __builtin_amdgcn_exp2f(t0[e]); e1[e] = __builtin_amdgcn_exp2f(t1[e]); }
;                 const f32x4 d0 = e0 * ms + ms, d1 = e1 * ms + ms;
; #pragma unroll
;                 for (int e = 0; e < 4; ++e) { i0[e] = __builtin_amdgcn_rcpf(d0[e]); i1[e] = __builtin_amdgcn_rcpf(d1[e]); }
;                 const f32x4 h0 = (g0 * u0) * i0, h1 = (g1 * u1) * i1;
;                 u32x4 w; w.x = cvt2_bf16(h0[0], h0[1]); w.y = cvt2_bf16(h0[2], h0[3]); w.z = cvt2_bf16(h1[0], h1[1]); w.w = cvt2_bf16(h1[2], h1[3]);
;                 *(u32x4*)(H + (size_t)row * ldh + col0) = w;
	v_mul_f32_e32 v105, v103, v123
	v_mul_f32_e32 v110, v110, v126
	v_mul_f32_e32 v111, v111, v127
	v_mul_f32_e32 v112, v112, v128
	v_mul_f32_e32 v113, v113, v129
	v_cvt_pk_bf16_f32 v104, v104, v105
	v_cvt_pk_bf16_f32 v105, v106, v107
	v_mad_i64_i32 v[106:107], s[10:11], v160, s13, v[118:119]
	v_cvt_pk_bf16_f32 v102, v110, v111
	v_cvt_pk_bf16_f32 v103, v112, v113
	v_lshl_add_u64 v[106:107], v[106:107], 0, v[120:121]
	global_store_dwordx4 v[106:107], v[102:105], off
	s_nop 1
	v_fmamk_f32 v102, v228, 0x3a800000, v231
	v_cmp_gt_f32_e32 vcc, s12, v102
	v_mul_f32_e32 v103, 0x4b800000, v102
	s_nop 0
	v_cndmask_b32_e32 v103, v102, v103, vcc
	v_rsq_f32_e32 v103, v103
	s_nop 0
	v_mul_f32_e32 v104, 0x45800000, v103
	v_cndmask_b32_e32 v103, v103, v104, vcc
	v_mul_f32_e32 v104, 0xbfb8aa3b, v103
	v_mul_f32_e32 v108, v98, v104
	v_mul_f32_e32 v109, v99, v104
	v_mul_f32_e32 v106, v100, v104
	v_mul_f32_e32 v107, v101, v104
	v_mul_f32_e32 v110, v96, v104
	v_mul_f32_e32 v111, v97, v104
	v_mul_f32_e32 v105, v95, v104
	v_mul_f32_e32 v104, v94, v104
	v_exp_f32_e32 v108, v108
	v_exp_f32_e32 v109, v109
	v_exp_f32_e32 v104, v104
	v_exp_f32_e32 v105, v105
	v_exp_f32_e32 v106, v106
	v_exp_f32_e32 v110, v110
	v_exp_f32_e32 v107, v107
	v_exp_f32_e32 v111, v111
	v_fma_f32 v108, v102, v108, v102
	v_fma_f32 v109, v102, v109, v102
	v_fma_f32 v106, v102, v106, v102
	v_fma_f32 v107, v102, v107, v102
	v_fma_f32 v110, v102, v110, v102
	v_fma_f32 v111, v102, v111, v102
	v_fma_f32 v103, v102, v105, v102
	v_fma_f32 v102, v102, v104, v102
	v_rcp_f32_e32 v104, v108
	v_rcp_f32_e32 v105, v109
	v_rcp_f32_e32 v102, v102
	v_rcp_f32_e32 v103, v103
	v_rcp_f32_e32 v106, v106
	v_rcp_f32_e32 v108, v110
	v_rcp_f32_e32 v107, v107
	v_rcp_f32_e32 v109, v111
	v_mul_f32_e32 v90, v90, v104
	v_mul_f32_e32 v91, v91, v105
	v_mul_f32_e32 v92, v92, v106
	v_mul_f32_e32 v93, v93, v107
	v_mul_f32_e32 v94, v88, v108
	v_mul_f32_e32 v95, v89, v109
	v_mul_f32_e32 v88, v86, v102
	v_mul_f32_e32 v89, v87, v103
	v_cvt_pk_bf16_f32 v86, v90, v91
	v_mad_i64_i32 v[90:91], s[10:11], v158, s13, v[118:119]
	v_cvt_pk_bf16_f32 v87, v92, v93
	v_cvt_pk_bf16_f32 v88, v88, v89
	v_cvt_pk_bf16_f32 v89, v94, v95
	v_lshl_add_u64 v[90:91], v[90:91], 0, v[120:121]
	global_store_dwordx4 v[90:91], v[86:89], off
	s_nop 1
	v_fmamk_f32 v86, v229, 0x3a800000, v231
	v_cmp_gt_f32_e32 vcc, s12, v86
	v_mul_f32_e32 v87, 0x4b800000, v86
	s_nop 0
	v_cndmask_b32_e32 v87, v86, v87, vcc
	v_rsq_f32_e32 v87, v87
	s_nop 0
	v_mul_f32_e32 v88, 0x45800000, v87
	v_cndmask_b32_e32 v87, v87, v88, vcc
	v_mul_f32_e32 v88, 0xbfb8aa3b, v87
	v_mul_f32_e32 v92, v82, v88
	v_mul_f32_e32 v93, v83, v88
	v_mul_f32_e32 v90, v84, v88
	v_mul_f32_e32 v91, v85, v88
	v_mul_f32_e32 v94, v80, v88
	v_mul_f32_e32 v95, v81, v88
	v_mul_f32_e32 v89, v79, v88
	v_mul_f32_e32 v88, v78, v88
	v_exp_f32_e32 v92, v92
	v_exp_f32_e32 v93, v93
	v_exp_f32_e32 v88, v88
	v_exp_f32_e32 v89, v89
	v_exp_f32_e32 v90, v90
	v_exp_f32_e32 v94, v94
	v_exp_f32_e32 v91, v91
	v_exp_f32_e32 v95, v95
	v_fma_f32 v92, v86, v92, v86
	v_fma_f32 v93, v86, v93, v86
	v_fma_f32 v90, v86, v90, v86
	v_fma_f32 v91, v86, v91, v86
	v_fma_f32 v94, v86, v94, v86
	v_fma_f32 v95, v86, v95, v86
	v_fma_f32 v87, v86, v89, v86
	v_fma_f32 v86, v86, v88, v86
	v_rcp_f32_e32 v88, v92
	v_rcp_f32_e32 v89, v93
	v_rcp_f32_e32 v86, v86
	v_rcp_f32_e32 v87, v87
	v_rcp_f32_e32 v90, v90
	v_rcp_f32_e32 v92, v94
	v_rcp_f32_e32 v91, v91
	v_rcp_f32_e32 v93, v95
	v_mul_f32_e32 v74, v74, v88
	v_mul_f32_e32 v75, v75, v89
	v_mul_f32_e32 v76, v76, v90
	v_mul_f32_e32 v77, v77, v91
	v_mul_f32_e32 v78, v72, v92
	v_mul_f32_e32 v79, v73, v93
	v_mul_f32_e32 v72, v70, v86
	v_mul_f32_e32 v73, v71, v87
	v_cvt_pk_bf16_f32 v70, v74, v75
	v_mad_i64_i32 v[74:75], s[10:11], v156, s13, v[118:119]
	v_cvt_pk_bf16_f32 v71, v76, v77
	v_cvt_pk_bf16_f32 v72, v72, v73
	v_cvt_pk_bf16_f32 v73, v78, v79
	v_lshl_add_u64 v[74:75], v[74:75], 0, v[120:121]
	global_store_dwordx4 v[74:75], v[70:73], off
	s_nop 1
	v_fmamk_f32 v70, v238, 0x3a800000, v231
	v_cmp_gt_f32_e32 vcc, s12, v70
	v_mul_f32_e32 v71, 0x4b800000, v70
	s_nop 0
	v_cndmask_b32_e32 v71, v70, v71, vcc
	v_rsq_f32_e32 v71, v71
	s_nop 0
	v_mul_f32_e32 v72, 0x45800000, v71
	v_cndmask_b32_e32 v71, v71, v72, vcc
	v_mul_f32_e32 v72, 0xbfb8aa3b, v71
	v_mul_f32_e32 v76, v66, v72
	v_mul_f32_e32 v77, v67, v72
	v_mul_f32_e32 v74, v68, v72
	v_mul_f32_e32 v75, v69, v72
	v_mul_f32_e32 v78, v64, v72
	v_mul_f32_e32 v79, v65, v72
	v_mul_f32_e32 v73, v63, v72
	v_mul_f32_e32 v72, v62, v72
	v_exp_f32_e32 v76, v76
	v_exp_f32_e32 v77, v77
	v_exp_f32_e32 v72, v72
	v_exp_f32_e32 v73, v73
	v_exp_f32_e32 v74, v74
	v_exp_f32_e32 v78, v78
	v_exp_f32_e32 v75, v75
	v_exp_f32_e32 v79, v79
	v_fma_f32 v76, v70, v76, v70
	v_fma_f32 v77, v70, v77, v70
	v_fma_f32 v74, v70, v74, v70
	v_fma_f32 v75, v70, v75, v70
	v_fma_f32 v78, v70, v78, v70
	v_fma_f32 v79, v70, v79, v70
	v_fma_f32 v71, v70, v73, v70
	v_fma_f32 v70, v70, v72, v70
	v_rcp_f32_e32 v72, v76
	v_rcp_f32_e32 v73, v77
	v_rcp_f32_e32 v70, v70
	v_rcp_f32_e32 v71, v71
	v_rcp_f32_e32 v74, v74
	v_rcp_f32_e32 v76, v78
	v_rcp_f32_e32 v75, v75
	v_rcp_f32_e32 v77, v79
	v_mul_f32_e32 v58, v58, v72
	v_mul_f32_e32 v59, v59, v73
	v_mul_f32_e32 v60, v60, v74
	v_mul_f32_e32 v61, v61, v75
	v_mul_f32_e32 v62, v56, v76
	v_mul_f32_e32 v63, v57, v77
	v_mul_f32_e32 v56, v54, v70
	v_mul_f32_e32 v57, v55, v71
	v_cvt_pk_bf16_f32 v54, v58, v59
	v_mad_i64_i32 v[58:59], s[10:11], v154, s13, v[118:119]
; #define PG8_BAR __builtin_amdgcn_s_barrier()
; __device__ __forceinline__ unsigned cvt2_bf16(float lo, float hi) { const f32x2n v = {lo, hi}; return __builtin_bit_cast(unsigned, __builtin_convertvector(v, bf16x2n)); }
; template <class Epi, class Sched, bool ALIGN_EPI = false, bool SP2 = false>
; __device__ __forceinline__ void gemm_phase(PG8_LAS unsigned char* lds, const Gemm g, const Sched& S, const Epi& E, const int tid_in) {
;     ...
;         if (!has_next) break;
; #pragma unroll
;         for (int a = 0; a < 2; ++a)
; #pragma unroll
;             for (int b = 0; b < 2; ++b)
; #pragma unroll
;                 for (int m = 0; m < 4; ++m)
; #pragma unroll
;                     for (int n = 0; n < 2; ++n) acc[a][b][m][n] = (f32x4){0.f, 0.f, 0.f, 0.f};
;         cur = nxt; cA = nA; cB = nB; ++ui;
;         if constexpr (ALIGN_EPI) { if (wr == 1) PG8_BAR; }
;     __device__ __forceinline__ void operator()(const f32x4 (&acc)[2][2][4][2], const Unit& u, int wr, int wc, int fr, int fq) const {
;     ...
;             for (int m = 0; m < 4; ++m) {
;                 const int row = row0 + ai * HALF + m * 16;
;                 const float ms = rs[ai][m] * (1.0f / 1024.0f) + RMS_EPS, c1 = -1.4426950408889634f * rsqrtf(ms);
;                 const f32x4 g0 = acc[ai][0][m][0], g1 = acc[ai][0][m][1], u0 = acc[ai][1][m][0], u1 = acc[ai][1][m][1];
;                 const f32x4 t0 = g0 * c1, t1 = g1 * c1; f32x4 e0, e1, i0, i1;
; #pragma unroll
;                 for (int e = 0; e < 4; ++e) { e0[e] = __builtin_amdgcn_exp2f(t0[e]); e1[e] = __builtin_amdgcn_exp2f(t1[e]); }
;                 const f32x4 d0 = e0 * ms + ms, d1 = e1 * ms + ms;
; #pragma unroll
;                 for (int e = 0; e < 4; ++e) { i0[e] = __builtin_amdgcn_rcpf(d0[e]); i1[e] = __builtin_amdgcn_rcpf(d1[e]); }
;                 const f32x4 h0 = (g0 * u0) * i0, h1 = (g1 * u1) * i1;
;                 u32x4 w; w.x = cvt2_bf16(h0[0], h0[1]); w.y = cvt2_bf16(h0[2], h0[3]); w.z = cvt2_bf16(h1[0], h1[1]); w.w = cvt2_bf16(h1[2], h1[3]);
;                 *(u32x4*)(H + (size_t)row * ldh + col0) = w;
	v_cvt_pk_bf16_f32 v55, v60, v61
	v_cvt_pk_bf16_f32 v56, v56, v57
	v_cvt_pk_bf16_f32 v57, v62, v63
	v_lshl_add_u64 v[58:59], v[58:59], 0, v[120:121]
	global_store_dwordx4 v[58:59], v[54:57], off
	s_nop 1
	v_fmamk_f32 v54, v239, 0x3a800000, v231
	v_cmp_gt_f32_e32 vcc, s12, v54
	v_mul_f32_e32 v55, 0x4b800000, v54
	s_nop 0
	v_cndmask_b32_e32 v55, v54, v55, vcc
	v_rsq_f32_e32 v55, v55
	s_nop 0
	v_mul_f32_e32 v56, 0x45800000, v55
	v_cndmask_b32_e32 v55, v55, v56, vcc
	v_mul_f32_e32 v56, 0xbfb8aa3b, v55
	v_mul_f32_e32 v60, v50, v56
	v_mul_f32_e32 v61, v51, v56
	v_mul_f32_e32 v58, v52, v56
	v_mul_f32_e32 v59, v53, v56
	v_mul_f32_e32 v62, v48, v56
	v_mul_f32_e32 v63, v49, v56
	v_mul_f32_e32 v57, v47, v56
	v_mul_f32_e32 v56, v46, v56
	v_exp_f32_e32 v60, v60
	v_exp_f32_e32 v61, v61
	v_exp_f32_e32 v56, v56
	v_exp_f32_e32 v57, v57
	v_exp_f32_e32 v58, v58
	v_exp_f32_e32 v62, v62
	v_exp_f32_e32 v59, v59
	v_exp_f32_e32 v63, v63
	v_fma_f32 v60, v54, v60, v54
	v_fma_f32 v61, v54, v61, v54
	v_fma_f32 v58, v54, v58, v54
	v_fma_f32 v59, v54, v59, v54
	v_fma_f32 v62, v54, v62, v54
	v_fma_f32 v63, v54, v63, v54
	v_fma_f32 v55, v54, v57, v54
	v_fma_f32 v54, v54, v56, v54
	v_rcp_f32_e32 v56, v60
	v_rcp_f32_e32 v57, v61
	v_rcp_f32_e32 v54, v54
	v_rcp_f32_e32 v55, v55
	v_rcp_f32_e32 v58, v58
	v_rcp_f32_e32 v60, v62
	v_rcp_f32_e32 v59, v59
	v_rcp_f32_e32 v61, v63
	v_mul_f32_e32 v42, v42, v56
	v_mul_f32_e32 v43, v43, v57
	v_mul_f32_e32 v44, v44, v58
	v_mul_f32_e32 v45, v45, v59
	v_mul_f32_e32 v46, v40, v60
	v_mul_f32_e32 v47, v41, v61
	v_mul_f32_e32 v40, v38, v54
	v_mul_f32_e32 v41, v39, v55
	v_cvt_pk_bf16_f32 v38, v42, v43
	v_mad_i64_i32 v[42:43], s[10:11], v152, s13, v[118:119]
	v_cvt_pk_bf16_f32 v39, v44, v45
	v_cvt_pk_bf16_f32 v40, v40, v41
	v_cvt_pk_bf16_f32 v41, v46, v47
	v_lshl_add_u64 v[42:43], v[42:43], 0, v[120:121]
	global_store_dwordx4 v[42:43], v[38:41], off
	s_nop 1
	v_fmamk_f32 v38, v240, 0x3a800000, v231
	v_cmp_gt_f32_e32 vcc, s12, v38
	v_mul_f32_e32 v39, 0x4b800000, v38
	s_nop 0
	v_cndmask_b32_e32 v39, v38, v39, vcc
	v_rsq_f32_e32 v39, v39
	s_nop 0
	v_mul_f32_e32 v40, 0x45800000, v39
	v_cndmask_b32_e32 v39, v39, v40, vcc
	v_mul_f32_e32 v40, 0xbfb8aa3b, v39
	v_mul_f32_e32 v44, v34, v40
	v_mul_f32_e32 v45, v35, v40
	v_mul_f32_e32 v42, v36, v40
	v_mul_f32_e32 v43, v37, v40
	v_mul_f32_e32 v46, v32, v40
	v_mul_f32_e32 v47, v33, v40
	v_mul_f32_e32 v41, v31, v40
	v_mul_f32_e32 v40, v30, v40
	v_exp_f32_e32 v44, v44
	v_exp_f32_e32 v45, v45
	v_exp_f32_e32 v40, v40
	v_exp_f32_e32 v41, v41
	v_exp_f32_e32 v42, v42
	v_exp_f32_e32 v46, v46
	v_exp_f32_e32 v43, v43
	v_exp_f32_e32 v47, v47
	v_fma_f32 v44, v38, v44, v38
	v_fma_f32 v45, v38, v45, v38
	v_fma_f32 v42, v38, v42, v38
	v_fma_f32 v43, v38, v43, v38
	v_fma_f32 v46, v38, v46, v38
	v_fma_f32 v47, v38, v47, v38
	v_fma_f32 v39, v38, v41, v38
	v_fma_f32 v38, v38, v40, v38
	v_rcp_f32_e32 v40, v44
	v_rcp_f32_e32 v41, v45
	v_rcp_f32_e32 v38, v38
	v_rcp_f32_e32 v39, v39
	v_rcp_f32_e32 v42, v42
	v_rcp_f32_e32 v44, v46
	v_rcp_f32_e32 v43, v43
	v_rcp_f32_e32 v45, v47
	v_mul_f32_e32 v26, v26, v40
	v_mul_f32_e32 v27, v27, v41
	v_mul_f32_e32 v28, v28, v42
	v_mul_f32_e32 v29, v29, v43
	v_mul_f32_e32 v30, v24, v44
	v_mul_f32_e32 v31, v25, v45
	v_mul_f32_e32 v24, v22, v38
	v_mul_f32_e32 v25, v23, v39
	v_cvt_pk_bf16_f32 v22, v26, v27
	v_mad_i64_i32 v[26:27], s[10:11], v150, s13, v[118:119]
	v_cvt_pk_bf16_f32 v23, v28, v29
	v_cvt_pk_bf16_f32 v24, v24, v25
	v_cvt_pk_bf16_f32 v25, v30, v31
	v_lshl_add_u64 v[26:27], v[26:27], 0, v[120:121]
	global_store_dwordx4 v[26:27], v[22:25], off
	s_nop 1
	v_fmamk_f32 v22, v241, 0x3a800000, v231
	v_cmp_gt_f32_e32 vcc, s12, v22
	v_mul_f32_e32 v23, 0x4b800000, v22
	s_nop 0
	v_cndmask_b32_e32 v23, v22, v23, vcc
	v_rsq_f32_e32 v23, v23
	s_nop 0
	v_mul_f32_e32 v24, 0x45800000, v23
	v_cndmask_b32_e32 v23, v23, v24, vcc
	v_mul_f32_e32 v24, 0xbfb8aa3b, v23
	v_mul_f32_e32 v28, v18, v24
	v_mul_f32_e32 v29, v19, v24
	v_mul_f32_e32 v26, v20, v24
	v_mul_f32_e32 v27, v21, v24
	v_mul_f32_e32 v30, v16, v24
	v_mul_f32_e32 v31, v17, v24
	v_mul_f32_e32 v25, v15, v24
	v_mul_f32_e32 v24, v14, v24
	v_exp_f32_e32 v28, v28
	v_exp_f32_e32 v29, v29
	v_exp_f32_e32 v24, v24
	v_exp_f32_e32 v25, v25
	v_exp_f32_e32 v26, v26
	v_exp_f32_e32 v30, v30
	v_exp_f32_e32 v27, v27
	v_exp_f32_e32 v31, v31
	v_fma_f32 v28, v22, v28, v22
	v_fma_f32 v29, v22, v29, v22
	s_andn2_b64 vcc, exec, s[36:37]
	v_fma_f32 v26, v22, v26, v22
	v_fma_f32 v27, v22, v27, v22
	v_fma_f32 v30, v22, v30, v22
	v_fma_f32 v31, v22, v31, v22
	v_fma_f32 v23, v22, v25, v22
	v_fma_f32 v22, v22, v24, v22
	v_rcp_f32_e32 v24, v28
	v_rcp_f32_e32 v25, v29
	v_rcp_f32_e32 v22, v22
	v_rcp_f32_e32 v23, v23
	v_rcp_f32_e32 v26, v26
	v_rcp_f32_e32 v28, v30
	v_rcp_f32_e32 v27, v27
	v_rcp_f32_e32 v29, v31
	v_mul_f32_e32 v10, v10, v24
	v_mul_f32_e32 v11, v11, v25
	v_mul_f32_e32 v12, v12, v26
	v_mul_f32_e32 v13, v13, v27
	v_mul_f32_e32 v14, v8, v28
	v_mul_f32_e32 v15, v9, v29
	v_mul_f32_e32 v8, v6, v22
	v_mul_f32_e32 v9, v7, v23
	v_cvt_pk_bf16_f32 v6, v10, v11
	v_mad_i64_i32 v[10:11], s[10:11], v145, s13, v[118:119]
	v_cvt_pk_bf16_f32 v7, v12, v13
	v_cvt_pk_bf16_f32 v8, v8, v9
	v_cvt_pk_bf16_f32 v9, v14, v15
	v_lshl_add_u64 v[10:11], v[10:11], 0, v[120:121]
	s_mov_b64 s[10:11], -1
	global_store_dwordx4 v[10:11], v[6:9], off
	s_cbranch_vccnz .LBB0_150
	s_andn2_b64 vcc, exec, s[4:5]
	s_cbranch_vccnz .LBB0_149
	s_barrier
	s_branch .LBB0_149
